# static chain placement + hand-scheduled RWKV-7 prompt step block (prefetched LDS operands, deferred butterfly output reduction)
# speedup vs baseline: 1.0249x; 1.0005x over previous
.LBB0_433:
	s_or_b64 exec, exec, s[4:5]
	v_lshl_add_u32 v17, v34, 2, s84
	v_add3_u32 v18, s84, v91, v92
	v_add_u32_e32 v25, 0x5000, v18
	v_bfe_u32 v19, v34, 2, 2
	ds_read2_b32 v[236:237], v25 offset0:0 offset1:16
	ds_read_b128 v[164:167], v17 offset:12288
	ds_read_b128 v[156:159], v17 offset:4096
	ds_read_b128 v[168:171], v17 offset:16384
	ds_read_b128 v[160:163], v17 offset:8192
	ds_read_b128 v[152:155], v17
	ds_read_b128 v[188:191], v17 offset:12544
	ds_read_b128 v[180:183], v17 offset:4352
	ds_read_b128 v[192:195], v17 offset:16640
	ds_read_b128 v[184:187], v17 offset:8448
	ds_read_b128 v[176:179], v17 offset:256
	s_waitcnt lgkmcnt(0)
	v_mul_f32_e32 v16, v164, v56
	v_fmac_f32_e32 v16, v165, v57
	v_fmac_f32_e32 v16, v166, v58
	v_fmac_f32_e32 v16, v167, v59
	v_mul_f32_e32 v20, v156, v236
	v_mul_f32_e32 v21, v157, v236
	v_add_f32_dpp v16, v16, v16 row_ror:8 row_mask:0xf bank_mask:0xf bound_ctrl:1
	v_mul_f32_e32 v22, v158, v236
	v_mul_f32_e32 v23, v159, v236
	v_add_f32_dpp v16, v16, v16 row_ror:4 row_mask:0xf bank_mask:0xf bound_ctrl:1
	ds_read2_b32 v[238:239], v25 offset0:32 offset1:48
	ds_read_b128 v[208:211], v17 offset:12800
	v_add_f32_dpp v16, v16, v16 row_ror:2 row_mask:0xf bank_mask:0xf bound_ctrl:1
	ds_read_b128 v[204:207], v17 offset:8704
	ds_read_b128 v[200:203], v17 offset:4608
	ds_read_b128 v[212:215], v17 offset:16896
	v_add_f32_dpp v16, v16, v16 row_ror:1 row_mask:0xf bank_mask:0xf bound_ctrl:1
	v_fma_f32 v20, -v168, v16, v20
	v_fma_f32 v21, -v169, v16, v21
	ds_read_b128 v[196:199], v17 offset:512
	v_fma_f32 v56, v160, v56, v20
	v_fma_f32 v22, -v170, v16, v22
	v_fma_f32 v57, v161, v57, v21
	v_fma_f32 v23, -v171, v16, v23
	v_fma_f32 v58, v162, v58, v22
	ds_read_b128 v[228:231], v17 offset:13056
	v_fma_f32 v59, v163, v59, v23
	v_mul_f32_e32 v16, v188, v56
	v_fmac_f32_e32 v16, v189, v57
	v_fmac_f32_e32 v16, v190, v58
	v_fmac_f32_e32 v16, v191, v59
	ds_read_b128 v[220:223], v17 offset:4864
	v_mul_f32_e32 v20, v180, v237
	v_mul_f32_e32 v21, v181, v237
	v_add_f32_dpp v16, v16, v16 row_ror:8 row_mask:0xf bank_mask:0xf bound_ctrl:1
	v_mul_f32_e32 v22, v182, v237
	v_mul_f32_e32 v23, v183, v237
	ds_read_b128 v[232:235], v17 offset:17152
	v_add_f32_dpp v16, v16, v16 row_ror:4 row_mask:0xf bank_mask:0xf bound_ctrl:1
	v_mul_f32_e32 v240, v152, v56
	v_fmac_f32_e32 v240, v153, v57
	v_add_f32_dpp v16, v16, v16 row_ror:2 row_mask:0xf bank_mask:0xf bound_ctrl:1
	v_fmac_f32_e32 v240, v154, v58
	ds_read_b128 v[224:227], v17 offset:8960
	v_fmac_f32_e32 v240, v155, v59
	v_add_f32_dpp v16, v16, v16 row_ror:1 row_mask:0xf bank_mask:0xf bound_ctrl:1
	v_fma_f32 v20, -v192, v16, v20
	v_fma_f32 v21, -v193, v16, v21
	v_fma_f32 v56, v184, v56, v20
	ds_read_b128 v[216:219], v17 offset:768
	v_fma_f32 v22, -v194, v16, v22
	v_fma_f32 v57, v185, v57, v21
	v_fma_f32 v23, -v195, v16, v23
	v_fma_f32 v58, v186, v58, v22
	v_fma_f32 v59, v187, v59, v23
	s_waitcnt lgkmcnt(0)
	v_mul_f32_e32 v16, v208, v56
	v_fmac_f32_e32 v16, v209, v57
	v_fmac_f32_e32 v16, v210, v58
	v_fmac_f32_e32 v16, v211, v59
	v_mul_f32_e32 v20, v200, v238
	v_mul_f32_e32 v21, v201, v238
	v_add_f32_dpp v16, v16, v16 row_ror:8 row_mask:0xf bank_mask:0xf bound_ctrl:1
	v_mul_f32_e32 v22, v202, v238
	v_mul_f32_e32 v23, v203, v238
	v_add_f32_dpp v16, v16, v16 row_ror:4 row_mask:0xf bank_mask:0xf bound_ctrl:1
	v_mul_f32_e32 v241, v176, v56
	v_fmac_f32_e32 v241, v177, v57
	v_add_f32_dpp v16, v16, v16 row_ror:2 row_mask:0xf bank_mask:0xf bound_ctrl:1
	ds_read2_b32 v[236:237], v25 offset0:64 offset1:80
	v_fmac_f32_e32 v241, v178, v58
	v_fmac_f32_e32 v241, v179, v59
	v_add_f32_dpp v16, v16, v16 row_ror:1 row_mask:0xf bank_mask:0xf bound_ctrl:1
	ds_read_b128 v[164:167], v17 offset:13312
	v_fma_f32 v20, -v212, v16, v20
	v_fma_f32 v21, -v213, v16, v21
	v_fma_f32 v56, v204, v56, v20
	ds_read_b128 v[156:159], v17 offset:5120
	v_fma_f32 v22, -v214, v16, v22
	v_fma_f32 v57, v205, v57, v21
	v_fma_f32 v23, -v215, v16, v23
	ds_read_b128 v[168:171], v17 offset:17408
	v_fma_f32 v58, v206, v58, v22
	v_fma_f32 v59, v207, v59, v23
	v_mul_f32_e32 v16, v228, v56
	v_fmac_f32_e32 v16, v229, v57
	ds_read_b128 v[160:163], v17 offset:9216
	v_fmac_f32_e32 v16, v230, v58
	v_fmac_f32_e32 v16, v231, v59
	v_mul_f32_e32 v20, v220, v239
	ds_read_b128 v[152:155], v17 offset:1024
	v_mul_f32_e32 v21, v221, v239
	v_add_f32_dpp v16, v16, v16 row_ror:8 row_mask:0xf bank_mask:0xf bound_ctrl:1
	v_mul_f32_e32 v22, v222, v239
	ds_read_b128 v[188:191], v17 offset:13568
	v_mul_f32_e32 v23, v223, v239
	v_add_f32_dpp v16, v16, v16 row_ror:4 row_mask:0xf bank_mask:0xf bound_ctrl:1
	v_mul_f32_e32 v242, v196, v56
	ds_read_b128 v[180:183], v17 offset:5376
	v_fmac_f32_e32 v242, v197, v57
	v_add_f32_dpp v16, v16, v16 row_ror:2 row_mask:0xf bank_mask:0xf bound_ctrl:1
	v_fmac_f32_e32 v242, v198, v58
	v_fmac_f32_e32 v242, v199, v59
	ds_read_b128 v[192:195], v17 offset:17664
	v_add_f32_dpp v16, v16, v16 row_ror:1 row_mask:0xf bank_mask:0xf bound_ctrl:1
	v_fma_f32 v20, -v232, v16, v20
	v_fma_f32 v21, -v233, v16, v21
	ds_read_b128 v[184:187], v17 offset:9472
	v_fma_f32 v56, v224, v56, v20
	v_fma_f32 v22, -v234, v16, v22
	v_fma_f32 v57, v225, v57, v21
	ds_read_b128 v[176:179], v17 offset:1280
	v_fma_f32 v23, -v235, v16, v23
	v_fma_f32 v58, v226, v58, v22
	v_fma_f32 v59, v227, v59, v23
	s_waitcnt lgkmcnt(0)
	v_mul_f32_e32 v16, v164, v56
	v_fmac_f32_e32 v16, v165, v57
	v_fmac_f32_e32 v16, v166, v58
	v_fmac_f32_e32 v16, v167, v59
	v_mul_f32_e32 v20, v156, v236
	v_mul_f32_e32 v21, v157, v236
	v_add_f32_dpp v16, v16, v16 row_ror:8 row_mask:0xf bank_mask:0xf bound_ctrl:1
	v_mul_f32_e32 v22, v158, v236
	v_mul_f32_e32 v23, v159, v236
	v_add_f32_dpp v16, v16, v16 row_ror:4 row_mask:0xf bank_mask:0xf bound_ctrl:1
	v_mul_f32_e32 v243, v216, v56
	v_fmac_f32_e32 v243, v217, v57
	v_add_f32_dpp v16, v16, v16 row_ror:2 row_mask:0xf bank_mask:0xf bound_ctrl:1
	ds_read2_b32 v[238:239], v25 offset0:96 offset1:112
	v_fmac_f32_e32 v243, v218, v58
	v_fmac_f32_e32 v243, v219, v59
	v_add_f32_dpp v16, v16, v16 row_ror:1 row_mask:0xf bank_mask:0xf bound_ctrl:1
	ds_read_b128 v[208:211], v17 offset:13824
	v_fma_f32 v20, -v168, v16, v20
	v_fma_f32 v21, -v169, v16, v21
	v_fma_f32 v56, v160, v56, v20
	ds_read_b128 v[200:203], v17 offset:5632
	v_fma_f32 v22, -v170, v16, v22
	v_fma_f32 v57, v161, v57, v21
	v_fma_f32 v23, -v171, v16, v23
	ds_read_b128 v[212:215], v17 offset:17920
	v_fma_f32 v58, v162, v58, v22
	v_fma_f32 v59, v163, v59, v23
	v_mul_f32_e32 v16, v188, v56
	v_fmac_f32_e32 v16, v189, v57
	ds_read_b128 v[204:207], v17 offset:9728
	v_fmac_f32_e32 v16, v190, v58
	v_fmac_f32_e32 v16, v191, v59
	v_mul_f32_e32 v20, v180, v237
	ds_read_b128 v[196:199], v17 offset:1536
	v_mul_f32_e32 v21, v181, v237
	v_add_f32_dpp v16, v16, v16 row_ror:8 row_mask:0xf bank_mask:0xf bound_ctrl:1
	v_mul_f32_e32 v22, v182, v237
	ds_read_b128 v[228:231], v17 offset:14080
	v_mul_f32_e32 v23, v183, v237
	v_add_f32_dpp v16, v16, v16 row_ror:4 row_mask:0xf bank_mask:0xf bound_ctrl:1
	v_mul_f32_e32 v244, v152, v56
	ds_read_b128 v[220:223], v17 offset:5888
	v_fmac_f32_e32 v244, v153, v57
	v_add_f32_dpp v16, v16, v16 row_ror:2 row_mask:0xf bank_mask:0xf bound_ctrl:1
	v_fmac_f32_e32 v244, v154, v58
	v_fmac_f32_e32 v244, v155, v59
	ds_read_b128 v[232:235], v17 offset:18176
	v_add_f32_dpp v16, v16, v16 row_ror:1 row_mask:0xf bank_mask:0xf bound_ctrl:1
	v_fma_f32 v20, -v192, v16, v20
	v_fma_f32 v21, -v193, v16, v21
	ds_read_b128 v[224:227], v17 offset:9984
	v_fma_f32 v56, v184, v56, v20
	v_fma_f32 v22, -v194, v16, v22
	v_fma_f32 v57, v185, v57, v21
	ds_read_b128 v[216:219], v17 offset:1792
	v_fma_f32 v23, -v195, v16, v23
	v_fma_f32 v58, v186, v58, v22
	v_fma_f32 v59, v187, v59, v23
	s_waitcnt lgkmcnt(0)
	v_mul_f32_e32 v16, v208, v56
	v_fmac_f32_e32 v16, v209, v57
	v_fmac_f32_e32 v16, v210, v58
	v_fmac_f32_e32 v16, v211, v59
	v_mul_f32_e32 v20, v200, v238
	v_mul_f32_e32 v21, v201, v238
	v_add_f32_dpp v16, v16, v16 row_ror:8 row_mask:0xf bank_mask:0xf bound_ctrl:1
	v_mul_f32_e32 v22, v202, v238
	v_mul_f32_e32 v23, v203, v238
	v_add_f32_dpp v16, v16, v16 row_ror:4 row_mask:0xf bank_mask:0xf bound_ctrl:1
	v_mul_f32_e32 v245, v176, v56
	v_fmac_f32_e32 v245, v177, v57
	v_add_f32_dpp v16, v16, v16 row_ror:2 row_mask:0xf bank_mask:0xf bound_ctrl:1
	ds_read2_b32 v[236:237], v25 offset0:128 offset1:144
	v_fmac_f32_e32 v245, v178, v58
	v_fmac_f32_e32 v245, v179, v59
	v_add_f32_dpp v16, v16, v16 row_ror:1 row_mask:0xf bank_mask:0xf bound_ctrl:1
	ds_read_b128 v[164:167], v17 offset:14336
	v_fma_f32 v20, -v212, v16, v20
	v_fma_f32 v21, -v213, v16, v21
	v_fma_f32 v56, v204, v56, v20
	ds_read_b128 v[156:159], v17 offset:6144
	v_fma_f32 v22, -v214, v16, v22
	v_fma_f32 v57, v205, v57, v21
	v_fma_f32 v23, -v215, v16, v23
	ds_read_b128 v[168:171], v17 offset:18432
	v_fma_f32 v58, v206, v58, v22
	v_fma_f32 v59, v207, v59, v23
	v_mul_f32_e32 v16, v228, v56
	v_fmac_f32_e32 v16, v229, v57
	ds_read_b128 v[160:163], v17 offset:10240
	v_fmac_f32_e32 v16, v230, v58
	v_fmac_f32_e32 v16, v231, v59
	v_mul_f32_e32 v20, v220, v239
	ds_read_b128 v[152:155], v17 offset:2048
	v_mul_f32_e32 v21, v221, v239
	v_add_f32_dpp v16, v16, v16 row_ror:8 row_mask:0xf bank_mask:0xf bound_ctrl:1
	v_mul_f32_e32 v22, v222, v239
	ds_read_b128 v[188:191], v17 offset:14592
	v_mul_f32_e32 v23, v223, v239
	v_add_f32_dpp v16, v16, v16 row_ror:4 row_mask:0xf bank_mask:0xf bound_ctrl:1
	v_mul_f32_e32 v246, v196, v56
	ds_read_b128 v[180:183], v17 offset:6400
	v_fmac_f32_e32 v246, v197, v57
	v_add_f32_dpp v16, v16, v16 row_ror:2 row_mask:0xf bank_mask:0xf bound_ctrl:1
	v_fmac_f32_e32 v246, v198, v58
	v_fmac_f32_e32 v246, v199, v59
	ds_read_b128 v[192:195], v17 offset:18688
	v_add_f32_dpp v16, v16, v16 row_ror:1 row_mask:0xf bank_mask:0xf bound_ctrl:1
	v_fma_f32 v20, -v232, v16, v20
	v_fma_f32 v21, -v233, v16, v21
	ds_read_b128 v[184:187], v17 offset:10496
	v_fma_f32 v56, v224, v56, v20
	v_fma_f32 v22, -v234, v16, v22
	v_fma_f32 v57, v225, v57, v21
	ds_read_b128 v[176:179], v17 offset:2304
	v_fma_f32 v23, -v235, v16, v23
	v_fma_f32 v58, v226, v58, v22
	v_fma_f32 v59, v227, v59, v23
	s_waitcnt lgkmcnt(0)
	v_mul_f32_e32 v16, v164, v56
	v_fmac_f32_e32 v16, v165, v57
	v_fmac_f32_e32 v16, v166, v58
	v_fmac_f32_e32 v16, v167, v59
	v_mul_f32_e32 v20, v156, v236
	v_mul_f32_e32 v21, v157, v236
	v_add_f32_dpp v16, v16, v16 row_ror:8 row_mask:0xf bank_mask:0xf bound_ctrl:1
	v_mul_f32_e32 v22, v158, v236
	v_mul_f32_e32 v23, v159, v236
	v_add_f32_dpp v16, v16, v16 row_ror:4 row_mask:0xf bank_mask:0xf bound_ctrl:1
	v_mul_f32_e32 v247, v216, v56
	v_fmac_f32_e32 v247, v217, v57
	v_add_f32_dpp v16, v16, v16 row_ror:2 row_mask:0xf bank_mask:0xf bound_ctrl:1
	ds_read2_b32 v[238:239], v25 offset0:160 offset1:176
	v_fmac_f32_e32 v247, v218, v58
	v_fmac_f32_e32 v247, v219, v59
	v_add_f32_dpp v16, v16, v16 row_ror:1 row_mask:0xf bank_mask:0xf bound_ctrl:1
	ds_read_b128 v[208:211], v17 offset:14848
	v_fma_f32 v20, -v168, v16, v20
	v_fma_f32 v21, -v169, v16, v21
	v_fma_f32 v56, v160, v56, v20
	ds_read_b128 v[200:203], v17 offset:6656
	v_fma_f32 v22, -v170, v16, v22
	v_fma_f32 v57, v161, v57, v21
	v_fma_f32 v23, -v171, v16, v23
	ds_read_b128 v[212:215], v17 offset:18944
	v_fma_f32 v58, v162, v58, v22
	v_fma_f32 v59, v163, v59, v23
	v_mul_f32_e32 v16, v188, v56
	v_fmac_f32_e32 v16, v189, v57
	ds_read_b128 v[204:207], v17 offset:10752
	v_fmac_f32_e32 v16, v190, v58
	v_fmac_f32_e32 v16, v191, v59
	v_mul_f32_e32 v20, v180, v237
	ds_read_b128 v[196:199], v17 offset:2560
	v_mul_f32_e32 v21, v181, v237
	v_add_f32_dpp v16, v16, v16 row_ror:8 row_mask:0xf bank_mask:0xf bound_ctrl:1
	v_mul_f32_e32 v22, v182, v237
	ds_read_b128 v[228:231], v17 offset:15104
	v_mul_f32_e32 v23, v183, v237
	v_add_f32_dpp v16, v16, v16 row_ror:4 row_mask:0xf bank_mask:0xf bound_ctrl:1
	v_mul_f32_e32 v248, v152, v56
	ds_read_b128 v[220:223], v17 offset:6912
	v_fmac_f32_e32 v248, v153, v57
	v_add_f32_dpp v16, v16, v16 row_ror:2 row_mask:0xf bank_mask:0xf bound_ctrl:1
	v_fmac_f32_e32 v248, v154, v58
	v_fmac_f32_e32 v248, v155, v59
	ds_read_b128 v[232:235], v17 offset:19200
	v_add_f32_dpp v16, v16, v16 row_ror:1 row_mask:0xf bank_mask:0xf bound_ctrl:1
	v_fma_f32 v20, -v192, v16, v20
	v_fma_f32 v21, -v193, v16, v21
	ds_read_b128 v[224:227], v17 offset:11008
	v_fma_f32 v56, v184, v56, v20
	v_fma_f32 v22, -v194, v16, v22
	v_fma_f32 v57, v185, v57, v21
	ds_read_b128 v[216:219], v17 offset:2816
	v_fma_f32 v23, -v195, v16, v23
	v_fma_f32 v58, v186, v58, v22
	v_fma_f32 v59, v187, v59, v23
	s_waitcnt lgkmcnt(0)
	v_mul_f32_e32 v16, v208, v56
	v_fmac_f32_e32 v16, v209, v57
	v_fmac_f32_e32 v16, v210, v58
	v_fmac_f32_e32 v16, v211, v59
	v_mul_f32_e32 v20, v200, v238
	v_mul_f32_e32 v21, v201, v238
	v_add_f32_dpp v16, v16, v16 row_ror:8 row_mask:0xf bank_mask:0xf bound_ctrl:1
	v_mul_f32_e32 v22, v202, v238
	v_mul_f32_e32 v23, v203, v238
	v_add_f32_dpp v16, v16, v16 row_ror:4 row_mask:0xf bank_mask:0xf bound_ctrl:1
	v_mul_f32_e32 v249, v176, v56
	v_fmac_f32_e32 v249, v177, v57
	v_add_f32_dpp v16, v16, v16 row_ror:2 row_mask:0xf bank_mask:0xf bound_ctrl:1
	ds_read2_b32 v[236:237], v25 offset0:192 offset1:208
	v_fmac_f32_e32 v249, v178, v58
	v_fmac_f32_e32 v249, v179, v59
	v_add_f32_dpp v16, v16, v16 row_ror:1 row_mask:0xf bank_mask:0xf bound_ctrl:1
	ds_read_b128 v[164:167], v17 offset:15360
	v_fma_f32 v20, -v212, v16, v20
	v_fma_f32 v21, -v213, v16, v21
	v_fma_f32 v56, v204, v56, v20
	ds_read_b128 v[156:159], v17 offset:7168
	v_fma_f32 v22, -v214, v16, v22
	v_fma_f32 v57, v205, v57, v21
	v_fma_f32 v23, -v215, v16, v23
	ds_read_b128 v[168:171], v17 offset:19456
	v_fma_f32 v58, v206, v58, v22
	v_fma_f32 v59, v207, v59, v23
	v_mul_f32_e32 v16, v228, v56
	v_fmac_f32_e32 v16, v229, v57
	ds_read_b128 v[160:163], v17 offset:11264
	v_fmac_f32_e32 v16, v230, v58
	v_fmac_f32_e32 v16, v231, v59
	v_mul_f32_e32 v20, v220, v239
	ds_read_b128 v[152:155], v17 offset:3072
	v_mul_f32_e32 v21, v221, v239
	v_add_f32_dpp v16, v16, v16 row_ror:8 row_mask:0xf bank_mask:0xf bound_ctrl:1
	v_mul_f32_e32 v22, v222, v239
	ds_read_b128 v[188:191], v17 offset:15616
	v_mul_f32_e32 v23, v223, v239
	v_add_f32_dpp v16, v16, v16 row_ror:4 row_mask:0xf bank_mask:0xf bound_ctrl:1
	v_mul_f32_e32 v150, v196, v56
	ds_read_b128 v[180:183], v17 offset:7424
	v_fmac_f32_e32 v150, v197, v57
	v_add_f32_dpp v16, v16, v16 row_ror:2 row_mask:0xf bank_mask:0xf bound_ctrl:1
	v_fmac_f32_e32 v150, v198, v58
	v_fmac_f32_e32 v150, v199, v59
	ds_read_b128 v[192:195], v17 offset:19712
	v_add_f32_dpp v16, v16, v16 row_ror:1 row_mask:0xf bank_mask:0xf bound_ctrl:1
	v_fma_f32 v20, -v232, v16, v20
	v_fma_f32 v21, -v233, v16, v21
	ds_read_b128 v[184:187], v17 offset:11520
	v_fma_f32 v56, v224, v56, v20
	v_fma_f32 v22, -v234, v16, v22
	v_fma_f32 v57, v225, v57, v21
	ds_read_b128 v[176:179], v17 offset:3328
	v_fma_f32 v23, -v235, v16, v23
	v_fma_f32 v58, v226, v58, v22
	v_fma_f32 v59, v227, v59, v23
	s_waitcnt lgkmcnt(0)
	v_mul_f32_e32 v16, v164, v56
	v_fmac_f32_e32 v16, v165, v57
	v_fmac_f32_e32 v16, v166, v58
	v_fmac_f32_e32 v16, v167, v59
	v_mul_f32_e32 v20, v156, v236
	v_mul_f32_e32 v21, v157, v236
	v_add_f32_dpp v16, v16, v16 row_ror:8 row_mask:0xf bank_mask:0xf bound_ctrl:1
	v_mul_f32_e32 v22, v158, v236
	v_mul_f32_e32 v23, v159, v236
	v_add_f32_dpp v16, v16, v16 row_ror:4 row_mask:0xf bank_mask:0xf bound_ctrl:1
	v_mul_f32_e32 v151, v216, v56
	v_fmac_f32_e32 v151, v217, v57
	v_add_f32_dpp v16, v16, v16 row_ror:2 row_mask:0xf bank_mask:0xf bound_ctrl:1
	ds_read2_b32 v[238:239], v25 offset0:224 offset1:240
	v_fmac_f32_e32 v151, v218, v58
	v_fmac_f32_e32 v151, v219, v59
	v_add_f32_dpp v16, v16, v16 row_ror:1 row_mask:0xf bank_mask:0xf bound_ctrl:1
	ds_read_b128 v[208:211], v17 offset:15872
	v_fma_f32 v20, -v168, v16, v20
	v_fma_f32 v21, -v169, v16, v21
	v_fma_f32 v56, v160, v56, v20
	ds_read_b128 v[200:203], v17 offset:7680
	v_fma_f32 v22, -v170, v16, v22
	v_fma_f32 v57, v161, v57, v21
	v_fma_f32 v23, -v171, v16, v23
	ds_read_b128 v[212:215], v17 offset:19968
	v_fma_f32 v58, v162, v58, v22
	v_fma_f32 v59, v163, v59, v23
	v_mul_f32_e32 v16, v188, v56
	v_fmac_f32_e32 v16, v189, v57
	ds_read_b128 v[204:207], v17 offset:11776
	v_fmac_f32_e32 v16, v190, v58
	v_fmac_f32_e32 v16, v191, v59
	v_mul_f32_e32 v20, v180, v237
	ds_read_b128 v[196:199], v17 offset:3584
	v_mul_f32_e32 v21, v181, v237
	v_add_f32_dpp v16, v16, v16 row_ror:8 row_mask:0xf bank_mask:0xf bound_ctrl:1
	v_mul_f32_e32 v22, v182, v237
	ds_read_b128 v[228:231], v17 offset:16128
	v_mul_f32_e32 v23, v183, v237
	v_add_f32_dpp v16, v16, v16 row_ror:4 row_mask:0xf bank_mask:0xf bound_ctrl:1
	v_mul_f32_e32 v26, v152, v56
	ds_read_b128 v[220:223], v17 offset:7936
	v_fmac_f32_e32 v26, v153, v57
	v_add_f32_dpp v16, v16, v16 row_ror:2 row_mask:0xf bank_mask:0xf bound_ctrl:1
	v_fmac_f32_e32 v26, v154, v58
	v_fmac_f32_e32 v26, v155, v59
	ds_read_b128 v[232:235], v17 offset:20224
	v_add_f32_dpp v16, v16, v16 row_ror:1 row_mask:0xf bank_mask:0xf bound_ctrl:1
	v_fma_f32 v20, -v192, v16, v20
	v_fma_f32 v21, -v193, v16, v21
	ds_read_b128 v[224:227], v17 offset:12032
	v_fma_f32 v56, v184, v56, v20
	v_fma_f32 v22, -v194, v16, v22
	v_fma_f32 v57, v185, v57, v21
	ds_read_b128 v[216:219], v17 offset:3840
	v_fma_f32 v23, -v195, v16, v23
	v_fma_f32 v58, v186, v58, v22
	v_fma_f32 v59, v187, v59, v23
	s_waitcnt lgkmcnt(0)
	v_mul_f32_e32 v16, v208, v56
	v_fmac_f32_e32 v16, v209, v57
	v_fmac_f32_e32 v16, v210, v58
	v_fmac_f32_e32 v16, v211, v59
	v_mul_f32_e32 v20, v200, v238
	v_mul_f32_e32 v21, v201, v238
	v_add_f32_dpp v16, v16, v16 row_ror:8 row_mask:0xf bank_mask:0xf bound_ctrl:1
	v_mul_f32_e32 v22, v202, v238
	v_mul_f32_e32 v23, v203, v238
	v_add_f32_dpp v16, v16, v16 row_ror:4 row_mask:0xf bank_mask:0xf bound_ctrl:1
	v_mul_f32_e32 v27, v176, v56
	v_fmac_f32_e32 v27, v177, v57
	v_add_f32_dpp v16, v16, v16 row_ror:2 row_mask:0xf bank_mask:0xf bound_ctrl:1
	v_fmac_f32_e32 v27, v178, v58
	v_fmac_f32_e32 v27, v179, v59
	v_add_f32_dpp v16, v16, v16 row_ror:1 row_mask:0xf bank_mask:0xf bound_ctrl:1
	v_fma_f32 v20, -v212, v16, v20
	v_fma_f32 v21, -v213, v16, v21
	v_fma_f32 v56, v204, v56, v20
	v_fma_f32 v22, -v214, v16, v22
	v_fma_f32 v57, v205, v57, v21
	v_fma_f32 v23, -v215, v16, v23
	v_fma_f32 v58, v206, v58, v22
	v_fma_f32 v59, v207, v59, v23
	v_mul_f32_e32 v16, v228, v56
	v_fmac_f32_e32 v16, v229, v57
	v_fmac_f32_e32 v16, v230, v58
	v_fmac_f32_e32 v16, v231, v59
	v_mul_f32_e32 v20, v220, v239
	v_mul_f32_e32 v21, v221, v239
	v_add_f32_dpp v16, v16, v16 row_ror:8 row_mask:0xf bank_mask:0xf bound_ctrl:1
	v_mul_f32_e32 v22, v222, v239
	v_mul_f32_e32 v23, v223, v239
	v_add_f32_dpp v16, v16, v16 row_ror:4 row_mask:0xf bank_mask:0xf bound_ctrl:1
	v_mul_f32_e32 v62, v196, v56
	v_fmac_f32_e32 v62, v197, v57
	v_add_f32_dpp v16, v16, v16 row_ror:2 row_mask:0xf bank_mask:0xf bound_ctrl:1
	v_fmac_f32_e32 v62, v198, v58
	v_fmac_f32_e32 v62, v199, v59
	v_add_f32_dpp v16, v16, v16 row_ror:1 row_mask:0xf bank_mask:0xf bound_ctrl:1
	v_fma_f32 v20, -v232, v16, v20
	v_fma_f32 v21, -v233, v16, v21
	v_fma_f32 v56, v224, v56, v20
	v_fma_f32 v22, -v234, v16, v22
	v_fma_f32 v57, v225, v57, v21
	v_fma_f32 v23, -v235, v16, v23
	v_fma_f32 v58, v226, v58, v22
	v_fma_f32 v59, v227, v59, v23
	v_mul_f32_e32 v63, v216, v56
	v_fmac_f32_e32 v63, v217, v57
	v_fmac_f32_e32 v63, v218, v58
	v_fmac_f32_e32 v63, v219, v59
	v_add_f32_dpp v240, v240, v240 row_ror:8 row_mask:0xf bank_mask:0x3
	v_add_f32_dpp v241, v241, v241 row_ror:8 row_mask:0xf bank_mask:0x3
	v_add_f32_dpp v242, v242, v242 row_ror:8 row_mask:0xf bank_mask:0x3
	v_add_f32_dpp v243, v243, v243 row_ror:8 row_mask:0xf bank_mask:0x3
	v_add_f32_dpp v244, v244, v244 row_ror:8 row_mask:0xf bank_mask:0x3
	v_add_f32_dpp v245, v245, v245 row_ror:8 row_mask:0xf bank_mask:0x3
	v_add_f32_dpp v246, v246, v246 row_ror:8 row_mask:0xf bank_mask:0x3
	v_add_f32_dpp v247, v247, v247 row_ror:8 row_mask:0xf bank_mask:0x3
	v_add_f32_dpp v240, v248, v248 row_ror:8 row_mask:0xf bank_mask:0xc
	v_add_f32_dpp v241, v249, v249 row_ror:8 row_mask:0xf bank_mask:0xc
	v_add_f32_dpp v242, v150, v150 row_ror:8 row_mask:0xf bank_mask:0xc
	v_add_f32_dpp v243, v151, v151 row_ror:8 row_mask:0xf bank_mask:0xc
	v_add_f32_dpp v244, v26, v26 row_ror:8 row_mask:0xf bank_mask:0xc
	v_add_f32_dpp v245, v27, v27 row_ror:8 row_mask:0xf bank_mask:0xc
	v_add_f32_dpp v246, v62, v62 row_ror:8 row_mask:0xf bank_mask:0xc
	v_add_f32_dpp v247, v63, v63 row_ror:8 row_mask:0xf bank_mask:0xc
	v_add_f32_dpp v240, v240, v240 row_ror:12 row_mask:0xf bank_mask:0x5
	v_add_f32_dpp v241, v241, v241 row_ror:12 row_mask:0xf bank_mask:0x5
	v_add_f32_dpp v242, v242, v242 row_ror:12 row_mask:0xf bank_mask:0x5
	v_add_f32_dpp v243, v243, v243 row_ror:12 row_mask:0xf bank_mask:0x5
	v_add_f32_dpp v240, v244, v244 row_ror:4 row_mask:0xf bank_mask:0xa
	v_add_f32_dpp v241, v245, v245 row_ror:4 row_mask:0xf bank_mask:0xa
	v_add_f32_dpp v242, v246, v246 row_ror:4 row_mask:0xf bank_mask:0xa
	v_add_f32_dpp v243, v247, v247 row_ror:4 row_mask:0xf bank_mask:0xa
	v_lshl_add_u32 v25, v34, 4, v18
	v_add_f32_dpp v240, v240, v240 quad_perm:[1,0,3,2] row_mask:0xf bank_mask:0xf
	v_add_f32_dpp v241, v241, v241 quad_perm:[1,0,3,2] row_mask:0xf bank_mask:0xf
	v_add_f32_dpp v242, v242, v242 quad_perm:[1,0,3,2] row_mask:0xf bank_mask:0xf
	v_add_f32_dpp v243, v243, v243 quad_perm:[1,0,3,2] row_mask:0xf bank_mask:0xf
	v_add_f32_dpp v240, v240, v240 quad_perm:[2,3,0,1] row_mask:0xf bank_mask:0xf
	v_add_f32_dpp v241, v241, v241 quad_perm:[2,3,0,1] row_mask:0xf bank_mask:0xf
	v_add_f32_dpp v242, v242, v242 quad_perm:[2,3,0,1] row_mask:0xf bank_mask:0xf
	v_add_f32_dpp v243, v243, v243 quad_perm:[2,3,0,1] row_mask:0xf bank_mask:0xf
	v_cmp_eq_u32_e32 vcc, 1, v19
	s_nop 1
	v_cndmask_b32_e32 v24, v240, v241, vcc
	v_cmp_eq_u32_e32 vcc, 2, v19
	s_nop 1
	v_cndmask_b32_e32 v24, v24, v242, vcc
	v_cmp_eq_u32_e32 vcc, 3, v19
	s_nop 1
	v_cndmask_b32_e32 v24, v24, v243, vcc
	ds_write_b32 v25, v24 offset:21504
	s_cmpk_eq_i32 s9, 0x7e0
	s_cbranch_scc1 .LBB0_451
	s_mov_b32 s13, s12
	s_mov_b32 s11, s9
	s_branch .LBB0_423

.LBB0_1416:
	s_or_b64 exec, exec, s[0:1]
	v_lshl_add_u32 v17, v36, 2, s25
	v_add3_u32 v18, s25, v93, v94
	v_add_u32_e32 v25, 0x5000, v18
	v_bfe_u32 v19, v36, 2, 2
	ds_read2_b32 v[236:237], v25 offset0:0 offset1:16
	ds_read_b128 v[164:167], v17 offset:12288
	ds_read_b128 v[156:159], v17 offset:4096
	ds_read_b128 v[168:171], v17 offset:16384
	ds_read_b128 v[160:163], v17 offset:8192
	ds_read_b128 v[152:155], v17
	ds_read_b128 v[188:191], v17 offset:12544
	ds_read_b128 v[180:183], v17 offset:4352
	ds_read_b128 v[192:195], v17 offset:16640
	ds_read_b128 v[184:187], v17 offset:8448
	ds_read_b128 v[176:179], v17 offset:256
	s_waitcnt lgkmcnt(0)
	v_mul_f32_e32 v16, v164, v58
	v_fmac_f32_e32 v16, v165, v59
	v_fmac_f32_e32 v16, v166, v60
	v_fmac_f32_e32 v16, v167, v61
	v_mul_f32_e32 v20, v156, v236
	v_mul_f32_e32 v21, v157, v236
	v_add_f32_dpp v16, v16, v16 row_ror:8 row_mask:0xf bank_mask:0xf bound_ctrl:1
	v_mul_f32_e32 v22, v158, v236
	v_mul_f32_e32 v23, v159, v236
	v_add_f32_dpp v16, v16, v16 row_ror:4 row_mask:0xf bank_mask:0xf bound_ctrl:1
	ds_read2_b32 v[238:239], v25 offset0:32 offset1:48
	ds_read_b128 v[208:211], v17 offset:12800
	v_add_f32_dpp v16, v16, v16 row_ror:2 row_mask:0xf bank_mask:0xf bound_ctrl:1
	ds_read_b128 v[204:207], v17 offset:8704
	ds_read_b128 v[200:203], v17 offset:4608
	ds_read_b128 v[212:215], v17 offset:16896
	v_add_f32_dpp v16, v16, v16 row_ror:1 row_mask:0xf bank_mask:0xf bound_ctrl:1
	v_fma_f32 v20, -v168, v16, v20
	v_fma_f32 v21, -v169, v16, v21
	ds_read_b128 v[196:199], v17 offset:512
	v_fma_f32 v58, v160, v58, v20
	v_fma_f32 v22, -v170, v16, v22
	v_fma_f32 v59, v161, v59, v21
	v_fma_f32 v23, -v171, v16, v23
	v_fma_f32 v60, v162, v60, v22
	ds_read_b128 v[228:231], v17 offset:13056
	v_fma_f32 v61, v163, v61, v23
	v_mul_f32_e32 v16, v188, v58
	v_fmac_f32_e32 v16, v189, v59
	v_fmac_f32_e32 v16, v190, v60
	v_fmac_f32_e32 v16, v191, v61
	ds_read_b128 v[220:223], v17 offset:4864
	v_mul_f32_e32 v20, v180, v237
	v_mul_f32_e32 v21, v181, v237
	v_add_f32_dpp v16, v16, v16 row_ror:8 row_mask:0xf bank_mask:0xf bound_ctrl:1
	v_mul_f32_e32 v22, v182, v237
	v_mul_f32_e32 v23, v183, v237
	ds_read_b128 v[232:235], v17 offset:17152
	v_add_f32_dpp v16, v16, v16 row_ror:4 row_mask:0xf bank_mask:0xf bound_ctrl:1
	v_mul_f32_e32 v240, v152, v58
	v_fmac_f32_e32 v240, v153, v59
	v_add_f32_dpp v16, v16, v16 row_ror:2 row_mask:0xf bank_mask:0xf bound_ctrl:1
	v_fmac_f32_e32 v240, v154, v60
	ds_read_b128 v[224:227], v17 offset:8960
	v_fmac_f32_e32 v240, v155, v61
	v_add_f32_dpp v16, v16, v16 row_ror:1 row_mask:0xf bank_mask:0xf bound_ctrl:1
	v_fma_f32 v20, -v192, v16, v20
	v_fma_f32 v21, -v193, v16, v21
	v_fma_f32 v58, v184, v58, v20
	ds_read_b128 v[216:219], v17 offset:768
	v_fma_f32 v22, -v194, v16, v22
	v_fma_f32 v59, v185, v59, v21
	v_fma_f32 v23, -v195, v16, v23
	v_fma_f32 v60, v186, v60, v22
	v_fma_f32 v61, v187, v61, v23
	s_waitcnt lgkmcnt(0)
	v_mul_f32_e32 v16, v208, v58
	v_fmac_f32_e32 v16, v209, v59
	v_fmac_f32_e32 v16, v210, v60
	v_fmac_f32_e32 v16, v211, v61
	v_mul_f32_e32 v20, v200, v238
	v_mul_f32_e32 v21, v201, v238
	v_add_f32_dpp v16, v16, v16 row_ror:8 row_mask:0xf bank_mask:0xf bound_ctrl:1
	v_mul_f32_e32 v22, v202, v238
	v_mul_f32_e32 v23, v203, v238
	v_add_f32_dpp v16, v16, v16 row_ror:4 row_mask:0xf bank_mask:0xf bound_ctrl:1
	v_mul_f32_e32 v241, v176, v58
	v_fmac_f32_e32 v241, v177, v59
	v_add_f32_dpp v16, v16, v16 row_ror:2 row_mask:0xf bank_mask:0xf bound_ctrl:1
	ds_read2_b32 v[236:237], v25 offset0:64 offset1:80
	v_fmac_f32_e32 v241, v178, v60
	v_fmac_f32_e32 v241, v179, v61
	v_add_f32_dpp v16, v16, v16 row_ror:1 row_mask:0xf bank_mask:0xf bound_ctrl:1
	ds_read_b128 v[164:167], v17 offset:13312
	v_fma_f32 v20, -v212, v16, v20
	v_fma_f32 v21, -v213, v16, v21
	v_fma_f32 v58, v204, v58, v20
	ds_read_b128 v[156:159], v17 offset:5120
	v_fma_f32 v22, -v214, v16, v22
	v_fma_f32 v59, v205, v59, v21
	v_fma_f32 v23, -v215, v16, v23
	ds_read_b128 v[168:171], v17 offset:17408
	v_fma_f32 v60, v206, v60, v22
	v_fma_f32 v61, v207, v61, v23
	v_mul_f32_e32 v16, v228, v58
	v_fmac_f32_e32 v16, v229, v59
	ds_read_b128 v[160:163], v17 offset:9216
	v_fmac_f32_e32 v16, v230, v60
	v_fmac_f32_e32 v16, v231, v61
	v_mul_f32_e32 v20, v220, v239
	ds_read_b128 v[152:155], v17 offset:1024
	v_mul_f32_e32 v21, v221, v239
	v_add_f32_dpp v16, v16, v16 row_ror:8 row_mask:0xf bank_mask:0xf bound_ctrl:1
	v_mul_f32_e32 v22, v222, v239
	ds_read_b128 v[188:191], v17 offset:13568
	v_mul_f32_e32 v23, v223, v239
	v_add_f32_dpp v16, v16, v16 row_ror:4 row_mask:0xf bank_mask:0xf bound_ctrl:1
	v_mul_f32_e32 v242, v196, v58
	ds_read_b128 v[180:183], v17 offset:5376
	v_fmac_f32_e32 v242, v197, v59
	v_add_f32_dpp v16, v16, v16 row_ror:2 row_mask:0xf bank_mask:0xf bound_ctrl:1
	v_fmac_f32_e32 v242, v198, v60
	v_fmac_f32_e32 v242, v199, v61
	ds_read_b128 v[192:195], v17 offset:17664
	v_add_f32_dpp v16, v16, v16 row_ror:1 row_mask:0xf bank_mask:0xf bound_ctrl:1
	v_fma_f32 v20, -v232, v16, v20
	v_fma_f32 v21, -v233, v16, v21
	ds_read_b128 v[184:187], v17 offset:9472
	v_fma_f32 v58, v224, v58, v20
	v_fma_f32 v22, -v234, v16, v22
	v_fma_f32 v59, v225, v59, v21
	ds_read_b128 v[176:179], v17 offset:1280
	v_fma_f32 v23, -v235, v16, v23
	v_fma_f32 v60, v226, v60, v22
	v_fma_f32 v61, v227, v61, v23
	s_waitcnt lgkmcnt(0)
	v_mul_f32_e32 v16, v164, v58
	v_fmac_f32_e32 v16, v165, v59
	v_fmac_f32_e32 v16, v166, v60
	v_fmac_f32_e32 v16, v167, v61
	v_mul_f32_e32 v20, v156, v236
	v_mul_f32_e32 v21, v157, v236
	v_add_f32_dpp v16, v16, v16 row_ror:8 row_mask:0xf bank_mask:0xf bound_ctrl:1
	v_mul_f32_e32 v22, v158, v236
	v_mul_f32_e32 v23, v159, v236
	v_add_f32_dpp v16, v16, v16 row_ror:4 row_mask:0xf bank_mask:0xf bound_ctrl:1
	v_mul_f32_e32 v243, v216, v58
	v_fmac_f32_e32 v243, v217, v59
	v_add_f32_dpp v16, v16, v16 row_ror:2 row_mask:0xf bank_mask:0xf bound_ctrl:1
	ds_read2_b32 v[238:239], v25 offset0:96 offset1:112
	v_fmac_f32_e32 v243, v218, v60
	v_fmac_f32_e32 v243, v219, v61
	v_add_f32_dpp v16, v16, v16 row_ror:1 row_mask:0xf bank_mask:0xf bound_ctrl:1
	ds_read_b128 v[208:211], v17 offset:13824
	v_fma_f32 v20, -v168, v16, v20
	v_fma_f32 v21, -v169, v16, v21
	v_fma_f32 v58, v160, v58, v20
	ds_read_b128 v[200:203], v17 offset:5632
	v_fma_f32 v22, -v170, v16, v22
	v_fma_f32 v59, v161, v59, v21
	v_fma_f32 v23, -v171, v16, v23
	ds_read_b128 v[212:215], v17 offset:17920
	v_fma_f32 v60, v162, v60, v22
	v_fma_f32 v61, v163, v61, v23
	v_mul_f32_e32 v16, v188, v58
	v_fmac_f32_e32 v16, v189, v59
	ds_read_b128 v[204:207], v17 offset:9728
	v_fmac_f32_e32 v16, v190, v60
	v_fmac_f32_e32 v16, v191, v61
	v_mul_f32_e32 v20, v180, v237
	ds_read_b128 v[196:199], v17 offset:1536
	v_mul_f32_e32 v21, v181, v237
	v_add_f32_dpp v16, v16, v16 row_ror:8 row_mask:0xf bank_mask:0xf bound_ctrl:1
	v_mul_f32_e32 v22, v182, v237
	ds_read_b128 v[228:231], v17 offset:14080
	v_mul_f32_e32 v23, v183, v237
	v_add_f32_dpp v16, v16, v16 row_ror:4 row_mask:0xf bank_mask:0xf bound_ctrl:1
	v_mul_f32_e32 v244, v152, v58
	ds_read_b128 v[220:223], v17 offset:5888
	v_fmac_f32_e32 v244, v153, v59
	v_add_f32_dpp v16, v16, v16 row_ror:2 row_mask:0xf bank_mask:0xf bound_ctrl:1
	v_fmac_f32_e32 v244, v154, v60
	v_fmac_f32_e32 v244, v155, v61
	ds_read_b128 v[232:235], v17 offset:18176
	v_add_f32_dpp v16, v16, v16 row_ror:1 row_mask:0xf bank_mask:0xf bound_ctrl:1
	v_fma_f32 v20, -v192, v16, v20
	v_fma_f32 v21, -v193, v16, v21
	ds_read_b128 v[224:227], v17 offset:9984
	v_fma_f32 v58, v184, v58, v20
	v_fma_f32 v22, -v194, v16, v22
	v_fma_f32 v59, v185, v59, v21
	ds_read_b128 v[216:219], v17 offset:1792
	v_fma_f32 v23, -v195, v16, v23
	v_fma_f32 v60, v186, v60, v22
	v_fma_f32 v61, v187, v61, v23
	s_waitcnt lgkmcnt(0)
	v_mul_f32_e32 v16, v208, v58
	v_fmac_f32_e32 v16, v209, v59
	v_fmac_f32_e32 v16, v210, v60
	v_fmac_f32_e32 v16, v211, v61
	v_mul_f32_e32 v20, v200, v238
	v_mul_f32_e32 v21, v201, v238
	v_add_f32_dpp v16, v16, v16 row_ror:8 row_mask:0xf bank_mask:0xf bound_ctrl:1
	v_mul_f32_e32 v22, v202, v238
	v_mul_f32_e32 v23, v203, v238
	v_add_f32_dpp v16, v16, v16 row_ror:4 row_mask:0xf bank_mask:0xf bound_ctrl:1
	v_mul_f32_e32 v245, v176, v58
	v_fmac_f32_e32 v245, v177, v59
	v_add_f32_dpp v16, v16, v16 row_ror:2 row_mask:0xf bank_mask:0xf bound_ctrl:1
	ds_read2_b32 v[236:237], v25 offset0:128 offset1:144
	v_fmac_f32_e32 v245, v178, v60
	v_fmac_f32_e32 v245, v179, v61
	v_add_f32_dpp v16, v16, v16 row_ror:1 row_mask:0xf bank_mask:0xf bound_ctrl:1
	ds_read_b128 v[164:167], v17 offset:14336
	v_fma_f32 v20, -v212, v16, v20
	v_fma_f32 v21, -v213, v16, v21
	v_fma_f32 v58, v204, v58, v20
	ds_read_b128 v[156:159], v17 offset:6144
	v_fma_f32 v22, -v214, v16, v22
	v_fma_f32 v59, v205, v59, v21
	v_fma_f32 v23, -v215, v16, v23
	ds_read_b128 v[168:171], v17 offset:18432
	v_fma_f32 v60, v206, v60, v22
	v_fma_f32 v61, v207, v61, v23
	v_mul_f32_e32 v16, v228, v58
	v_fmac_f32_e32 v16, v229, v59
	ds_read_b128 v[160:163], v17 offset:10240
	v_fmac_f32_e32 v16, v230, v60
	v_fmac_f32_e32 v16, v231, v61
	v_mul_f32_e32 v20, v220, v239
	ds_read_b128 v[152:155], v17 offset:2048
	v_mul_f32_e32 v21, v221, v239
	v_add_f32_dpp v16, v16, v16 row_ror:8 row_mask:0xf bank_mask:0xf bound_ctrl:1
	v_mul_f32_e32 v22, v222, v239
	ds_read_b128 v[188:191], v17 offset:14592
	v_mul_f32_e32 v23, v223, v239
	v_add_f32_dpp v16, v16, v16 row_ror:4 row_mask:0xf bank_mask:0xf bound_ctrl:1
	v_mul_f32_e32 v246, v196, v58
	ds_read_b128 v[180:183], v17 offset:6400
	v_fmac_f32_e32 v246, v197, v59
	v_add_f32_dpp v16, v16, v16 row_ror:2 row_mask:0xf bank_mask:0xf bound_ctrl:1
	v_fmac_f32_e32 v246, v198, v60
	v_fmac_f32_e32 v246, v199, v61
	ds_read_b128 v[192:195], v17 offset:18688
	v_add_f32_dpp v16, v16, v16 row_ror:1 row_mask:0xf bank_mask:0xf bound_ctrl:1
	v_fma_f32 v20, -v232, v16, v20
	v_fma_f32 v21, -v233, v16, v21
	ds_read_b128 v[184:187], v17 offset:10496
	v_fma_f32 v58, v224, v58, v20
	v_fma_f32 v22, -v234, v16, v22
	v_fma_f32 v59, v225, v59, v21
	ds_read_b128 v[176:179], v17 offset:2304
	v_fma_f32 v23, -v235, v16, v23
	v_fma_f32 v60, v226, v60, v22
	v_fma_f32 v61, v227, v61, v23
	s_waitcnt lgkmcnt(0)
	v_mul_f32_e32 v16, v164, v58
	v_fmac_f32_e32 v16, v165, v59
	v_fmac_f32_e32 v16, v166, v60
	v_fmac_f32_e32 v16, v167, v61
	v_mul_f32_e32 v20, v156, v236
	v_mul_f32_e32 v21, v157, v236
	v_add_f32_dpp v16, v16, v16 row_ror:8 row_mask:0xf bank_mask:0xf bound_ctrl:1
	v_mul_f32_e32 v22, v158, v236
	v_mul_f32_e32 v23, v159, v236
	v_add_f32_dpp v16, v16, v16 row_ror:4 row_mask:0xf bank_mask:0xf bound_ctrl:1
	v_mul_f32_e32 v247, v216, v58
	v_fmac_f32_e32 v247, v217, v59
	v_add_f32_dpp v16, v16, v16 row_ror:2 row_mask:0xf bank_mask:0xf bound_ctrl:1
	ds_read2_b32 v[238:239], v25 offset0:160 offset1:176
	v_fmac_f32_e32 v247, v218, v60
	v_fmac_f32_e32 v247, v219, v61
	v_add_f32_dpp v16, v16, v16 row_ror:1 row_mask:0xf bank_mask:0xf bound_ctrl:1
	ds_read_b128 v[208:211], v17 offset:14848
	v_fma_f32 v20, -v168, v16, v20
	v_fma_f32 v21, -v169, v16, v21
	v_fma_f32 v58, v160, v58, v20
	ds_read_b128 v[200:203], v17 offset:6656
	v_fma_f32 v22, -v170, v16, v22
	v_fma_f32 v59, v161, v59, v21
	v_fma_f32 v23, -v171, v16, v23
	ds_read_b128 v[212:215], v17 offset:18944
	v_fma_f32 v60, v162, v60, v22
	v_fma_f32 v61, v163, v61, v23
	v_mul_f32_e32 v16, v188, v58
	v_fmac_f32_e32 v16, v189, v59
	ds_read_b128 v[204:207], v17 offset:10752
	v_fmac_f32_e32 v16, v190, v60
	v_fmac_f32_e32 v16, v191, v61
	v_mul_f32_e32 v20, v180, v237
	ds_read_b128 v[196:199], v17 offset:2560
	v_mul_f32_e32 v21, v181, v237
	v_add_f32_dpp v16, v16, v16 row_ror:8 row_mask:0xf bank_mask:0xf bound_ctrl:1
	v_mul_f32_e32 v22, v182, v237
	ds_read_b128 v[228:231], v17 offset:15104
	v_mul_f32_e32 v23, v183, v237
	v_add_f32_dpp v16, v16, v16 row_ror:4 row_mask:0xf bank_mask:0xf bound_ctrl:1
	v_mul_f32_e32 v248, v152, v58
	ds_read_b128 v[220:223], v17 offset:6912
	v_fmac_f32_e32 v248, v153, v59
	v_add_f32_dpp v16, v16, v16 row_ror:2 row_mask:0xf bank_mask:0xf bound_ctrl:1
	v_fmac_f32_e32 v248, v154, v60
	v_fmac_f32_e32 v248, v155, v61
	ds_read_b128 v[232:235], v17 offset:19200
	v_add_f32_dpp v16, v16, v16 row_ror:1 row_mask:0xf bank_mask:0xf bound_ctrl:1
	v_fma_f32 v20, -v192, v16, v20
	v_fma_f32 v21, -v193, v16, v21
	ds_read_b128 v[224:227], v17 offset:11008
	v_fma_f32 v58, v184, v58, v20
	v_fma_f32 v22, -v194, v16, v22
	v_fma_f32 v59, v185, v59, v21
	ds_read_b128 v[216:219], v17 offset:2816
	v_fma_f32 v23, -v195, v16, v23
	v_fma_f32 v60, v186, v60, v22
	v_fma_f32 v61, v187, v61, v23
	s_waitcnt lgkmcnt(0)
	v_mul_f32_e32 v16, v208, v58
	v_fmac_f32_e32 v16, v209, v59
	v_fmac_f32_e32 v16, v210, v60
	v_fmac_f32_e32 v16, v211, v61
	v_mul_f32_e32 v20, v200, v238
	v_mul_f32_e32 v21, v201, v238
	v_add_f32_dpp v16, v16, v16 row_ror:8 row_mask:0xf bank_mask:0xf bound_ctrl:1
	v_mul_f32_e32 v22, v202, v238
	v_mul_f32_e32 v23, v203, v238
	v_add_f32_dpp v16, v16, v16 row_ror:4 row_mask:0xf bank_mask:0xf bound_ctrl:1
	v_mul_f32_e32 v249, v176, v58
	v_fmac_f32_e32 v249, v177, v59
	v_add_f32_dpp v16, v16, v16 row_ror:2 row_mask:0xf bank_mask:0xf bound_ctrl:1
	ds_read2_b32 v[236:237], v25 offset0:192 offset1:208
	v_fmac_f32_e32 v249, v178, v60
	v_fmac_f32_e32 v249, v179, v61
	v_add_f32_dpp v16, v16, v16 row_ror:1 row_mask:0xf bank_mask:0xf bound_ctrl:1
	ds_read_b128 v[164:167], v17 offset:15360
	v_fma_f32 v20, -v212, v16, v20
	v_fma_f32 v21, -v213, v16, v21
	v_fma_f32 v58, v204, v58, v20
	ds_read_b128 v[156:159], v17 offset:7168
	v_fma_f32 v22, -v214, v16, v22
	v_fma_f32 v59, v205, v59, v21
	v_fma_f32 v23, -v215, v16, v23
	ds_read_b128 v[168:171], v17 offset:19456
	v_fma_f32 v60, v206, v60, v22
	v_fma_f32 v61, v207, v61, v23
	v_mul_f32_e32 v16, v228, v58
	v_fmac_f32_e32 v16, v229, v59
	ds_read_b128 v[160:163], v17 offset:11264
	v_fmac_f32_e32 v16, v230, v60
	v_fmac_f32_e32 v16, v231, v61
	v_mul_f32_e32 v20, v220, v239
	ds_read_b128 v[152:155], v17 offset:3072
	v_mul_f32_e32 v21, v221, v239
	v_add_f32_dpp v16, v16, v16 row_ror:8 row_mask:0xf bank_mask:0xf bound_ctrl:1
	v_mul_f32_e32 v22, v222, v239
	ds_read_b128 v[188:191], v17 offset:15616
	v_mul_f32_e32 v23, v223, v239
	v_add_f32_dpp v16, v16, v16 row_ror:4 row_mask:0xf bank_mask:0xf bound_ctrl:1
	v_mul_f32_e32 v150, v196, v58
	ds_read_b128 v[180:183], v17 offset:7424
	v_fmac_f32_e32 v150, v197, v59
	v_add_f32_dpp v16, v16, v16 row_ror:2 row_mask:0xf bank_mask:0xf bound_ctrl:1
	v_fmac_f32_e32 v150, v198, v60
	v_fmac_f32_e32 v150, v199, v61
	ds_read_b128 v[192:195], v17 offset:19712
	v_add_f32_dpp v16, v16, v16 row_ror:1 row_mask:0xf bank_mask:0xf bound_ctrl:1
	v_fma_f32 v20, -v232, v16, v20
	v_fma_f32 v21, -v233, v16, v21
	ds_read_b128 v[184:187], v17 offset:11520
	v_fma_f32 v58, v224, v58, v20
	v_fma_f32 v22, -v234, v16, v22
	v_fma_f32 v59, v225, v59, v21
	ds_read_b128 v[176:179], v17 offset:3328
	v_fma_f32 v23, -v235, v16, v23
	v_fma_f32 v60, v226, v60, v22
	v_fma_f32 v61, v227, v61, v23
	s_waitcnt lgkmcnt(0)
	v_mul_f32_e32 v16, v164, v58
	v_fmac_f32_e32 v16, v165, v59
	v_fmac_f32_e32 v16, v166, v60
	v_fmac_f32_e32 v16, v167, v61
	v_mul_f32_e32 v20, v156, v236
	v_mul_f32_e32 v21, v157, v236
	v_add_f32_dpp v16, v16, v16 row_ror:8 row_mask:0xf bank_mask:0xf bound_ctrl:1
	v_mul_f32_e32 v22, v158, v236
	v_mul_f32_e32 v23, v159, v236
	v_add_f32_dpp v16, v16, v16 row_ror:4 row_mask:0xf bank_mask:0xf bound_ctrl:1
	v_mul_f32_e32 v151, v216, v58
	v_fmac_f32_e32 v151, v217, v59
	v_add_f32_dpp v16, v16, v16 row_ror:2 row_mask:0xf bank_mask:0xf bound_ctrl:1
	ds_read2_b32 v[238:239], v25 offset0:224 offset1:240
	v_fmac_f32_e32 v151, v218, v60
	v_fmac_f32_e32 v151, v219, v61
	v_add_f32_dpp v16, v16, v16 row_ror:1 row_mask:0xf bank_mask:0xf bound_ctrl:1
	ds_read_b128 v[208:211], v17 offset:15872
	v_fma_f32 v20, -v168, v16, v20
	v_fma_f32 v21, -v169, v16, v21
	v_fma_f32 v58, v160, v58, v20
	ds_read_b128 v[200:203], v17 offset:7680
	v_fma_f32 v22, -v170, v16, v22
	v_fma_f32 v59, v161, v59, v21
	v_fma_f32 v23, -v171, v16, v23
	ds_read_b128 v[212:215], v17 offset:19968
	v_fma_f32 v60, v162, v60, v22
	v_fma_f32 v61, v163, v61, v23
	v_mul_f32_e32 v16, v188, v58
	v_fmac_f32_e32 v16, v189, v59
	ds_read_b128 v[204:207], v17 offset:11776
	v_fmac_f32_e32 v16, v190, v60
	v_fmac_f32_e32 v16, v191, v61
	v_mul_f32_e32 v20, v180, v237
	ds_read_b128 v[196:199], v17 offset:3584
	v_mul_f32_e32 v21, v181, v237
	v_add_f32_dpp v16, v16, v16 row_ror:8 row_mask:0xf bank_mask:0xf bound_ctrl:1
	v_mul_f32_e32 v22, v182, v237
	ds_read_b128 v[228:231], v17 offset:16128
	v_mul_f32_e32 v23, v183, v237
	v_add_f32_dpp v16, v16, v16 row_ror:4 row_mask:0xf bank_mask:0xf bound_ctrl:1
	v_mul_f32_e32 v26, v152, v58
	ds_read_b128 v[220:223], v17 offset:7936
	v_fmac_f32_e32 v26, v153, v59
	v_add_f32_dpp v16, v16, v16 row_ror:2 row_mask:0xf bank_mask:0xf bound_ctrl:1
	v_fmac_f32_e32 v26, v154, v60
	v_fmac_f32_e32 v26, v155, v61
	ds_read_b128 v[232:235], v17 offset:20224
	v_add_f32_dpp v16, v16, v16 row_ror:1 row_mask:0xf bank_mask:0xf bound_ctrl:1
	v_fma_f32 v20, -v192, v16, v20
	v_fma_f32 v21, -v193, v16, v21
	ds_read_b128 v[224:227], v17 offset:12032
	v_fma_f32 v58, v184, v58, v20
	v_fma_f32 v22, -v194, v16, v22
	v_fma_f32 v59, v185, v59, v21
	ds_read_b128 v[216:219], v17 offset:3840
	v_fma_f32 v23, -v195, v16, v23
	v_fma_f32 v60, v186, v60, v22
	v_fma_f32 v61, v187, v61, v23
	s_waitcnt lgkmcnt(0)
	v_mul_f32_e32 v16, v208, v58
	v_fmac_f32_e32 v16, v209, v59
	v_fmac_f32_e32 v16, v210, v60
	v_fmac_f32_e32 v16, v211, v61
	v_mul_f32_e32 v20, v200, v238
	v_mul_f32_e32 v21, v201, v238
	v_add_f32_dpp v16, v16, v16 row_ror:8 row_mask:0xf bank_mask:0xf bound_ctrl:1
	v_mul_f32_e32 v22, v202, v238
	v_mul_f32_e32 v23, v203, v238
	v_add_f32_dpp v16, v16, v16 row_ror:4 row_mask:0xf bank_mask:0xf bound_ctrl:1
	v_mul_f32_e32 v27, v176, v58
	v_fmac_f32_e32 v27, v177, v59
	v_add_f32_dpp v16, v16, v16 row_ror:2 row_mask:0xf bank_mask:0xf bound_ctrl:1
	v_fmac_f32_e32 v27, v178, v60
	v_fmac_f32_e32 v27, v179, v61
	v_add_f32_dpp v16, v16, v16 row_ror:1 row_mask:0xf bank_mask:0xf bound_ctrl:1
	v_fma_f32 v20, -v212, v16, v20
	v_fma_f32 v21, -v213, v16, v21
	v_fma_f32 v58, v204, v58, v20
	v_fma_f32 v22, -v214, v16, v22
	v_fma_f32 v59, v205, v59, v21
	v_fma_f32 v23, -v215, v16, v23
	v_fma_f32 v60, v206, v60, v22
	v_fma_f32 v61, v207, v61, v23
	v_mul_f32_e32 v16, v228, v58
	v_fmac_f32_e32 v16, v229, v59
	v_fmac_f32_e32 v16, v230, v60
	v_fmac_f32_e32 v16, v231, v61
	v_mul_f32_e32 v20, v220, v239
	v_mul_f32_e32 v21, v221, v239
	v_add_f32_dpp v16, v16, v16 row_ror:8 row_mask:0xf bank_mask:0xf bound_ctrl:1
	v_mul_f32_e32 v22, v222, v239
	v_mul_f32_e32 v23, v223, v239
	v_add_f32_dpp v16, v16, v16 row_ror:4 row_mask:0xf bank_mask:0xf bound_ctrl:1
	v_mul_f32_e32 v62, v196, v58
	v_fmac_f32_e32 v62, v197, v59
	v_add_f32_dpp v16, v16, v16 row_ror:2 row_mask:0xf bank_mask:0xf bound_ctrl:1
	v_fmac_f32_e32 v62, v198, v60
	v_fmac_f32_e32 v62, v199, v61
	v_add_f32_dpp v16, v16, v16 row_ror:1 row_mask:0xf bank_mask:0xf bound_ctrl:1
	v_fma_f32 v20, -v232, v16, v20
	v_fma_f32 v21, -v233, v16, v21
	v_fma_f32 v58, v224, v58, v20
	v_fma_f32 v22, -v234, v16, v22
	v_fma_f32 v59, v225, v59, v21
	v_fma_f32 v23, -v235, v16, v23
	v_fma_f32 v60, v226, v60, v22
	v_fma_f32 v61, v227, v61, v23
	v_mul_f32_e32 v63, v216, v58
	v_fmac_f32_e32 v63, v217, v59
	v_fmac_f32_e32 v63, v218, v60
	v_fmac_f32_e32 v63, v219, v61
	v_add_f32_dpp v240, v240, v240 row_ror:8 row_mask:0xf bank_mask:0x3
	v_add_f32_dpp v241, v241, v241 row_ror:8 row_mask:0xf bank_mask:0x3
	v_add_f32_dpp v242, v242, v242 row_ror:8 row_mask:0xf bank_mask:0x3
	v_add_f32_dpp v243, v243, v243 row_ror:8 row_mask:0xf bank_mask:0x3
	v_add_f32_dpp v244, v244, v244 row_ror:8 row_mask:0xf bank_mask:0x3
	v_add_f32_dpp v245, v245, v245 row_ror:8 row_mask:0xf bank_mask:0x3
	v_add_f32_dpp v246, v246, v246 row_ror:8 row_mask:0xf bank_mask:0x3
	v_add_f32_dpp v247, v247, v247 row_ror:8 row_mask:0xf bank_mask:0x3
	v_add_f32_dpp v240, v248, v248 row_ror:8 row_mask:0xf bank_mask:0xc
	v_add_f32_dpp v241, v249, v249 row_ror:8 row_mask:0xf bank_mask:0xc
	v_add_f32_dpp v242, v150, v150 row_ror:8 row_mask:0xf bank_mask:0xc
	v_add_f32_dpp v243, v151, v151 row_ror:8 row_mask:0xf bank_mask:0xc
	v_add_f32_dpp v244, v26, v26 row_ror:8 row_mask:0xf bank_mask:0xc
	v_add_f32_dpp v245, v27, v27 row_ror:8 row_mask:0xf bank_mask:0xc
	v_add_f32_dpp v246, v62, v62 row_ror:8 row_mask:0xf bank_mask:0xc
	v_add_f32_dpp v247, v63, v63 row_ror:8 row_mask:0xf bank_mask:0xc
	v_add_f32_dpp v240, v240, v240 row_ror:12 row_mask:0xf bank_mask:0x5
	v_add_f32_dpp v241, v241, v241 row_ror:12 row_mask:0xf bank_mask:0x5
	v_add_f32_dpp v242, v242, v242 row_ror:12 row_mask:0xf bank_mask:0x5
	v_add_f32_dpp v243, v243, v243 row_ror:12 row_mask:0xf bank_mask:0x5
	v_add_f32_dpp v240, v244, v244 row_ror:4 row_mask:0xf bank_mask:0xa
	v_add_f32_dpp v241, v245, v245 row_ror:4 row_mask:0xf bank_mask:0xa
	v_add_f32_dpp v242, v246, v246 row_ror:4 row_mask:0xf bank_mask:0xa
	v_add_f32_dpp v243, v247, v247 row_ror:4 row_mask:0xf bank_mask:0xa
	v_lshl_add_u32 v25, v36, 4, v18
	v_add_f32_dpp v240, v240, v240 quad_perm:[1,0,3,2] row_mask:0xf bank_mask:0xf
	v_add_f32_dpp v241, v241, v241 quad_perm:[1,0,3,2] row_mask:0xf bank_mask:0xf
	v_add_f32_dpp v242, v242, v242 quad_perm:[1,0,3,2] row_mask:0xf bank_mask:0xf
	v_add_f32_dpp v243, v243, v243 quad_perm:[1,0,3,2] row_mask:0xf bank_mask:0xf
	v_add_f32_dpp v240, v240, v240 quad_perm:[2,3,0,1] row_mask:0xf bank_mask:0xf
	v_add_f32_dpp v241, v241, v241 quad_perm:[2,3,0,1] row_mask:0xf bank_mask:0xf
	v_add_f32_dpp v242, v242, v242 quad_perm:[2,3,0,1] row_mask:0xf bank_mask:0xf
	v_add_f32_dpp v243, v243, v243 quad_perm:[2,3,0,1] row_mask:0xf bank_mask:0xf
	v_cmp_eq_u32_e32 vcc, 1, v19
	s_nop 1
	v_cndmask_b32_e32 v24, v240, v241, vcc
	v_cmp_eq_u32_e32 vcc, 2, v19
	s_nop 1
	v_cndmask_b32_e32 v24, v24, v242, vcc
	v_cmp_eq_u32_e32 vcc, 3, v19
	s_nop 1
	v_cndmask_b32_e32 v24, v24, v243, vcc
	ds_write_b32 v25, v24 offset:21504
	s_cmpk_eq_i32 s9, 0x7e0
	s_cbranch_scc1 .LBB0_1434
	s_mov_b32 s21, s24
	s_mov_b32 s20, s9
	s_branch .LBB0_1406
